# rwkv2 role 2 wave 5 beta: MVs = Mak*V reads/MFMAs/writes batched
# speedup vs baseline: 1.0022x; 1.0022x over previous
; #define MFMA16(a, b, c) __builtin_amdgcn_mfma_f32_16x16x32_bf16((a), (b), (c), 0, 0, 0)
; #define TRI_ROW(dst, base, t) do { dst[0] = *(const f32x4*)(Mx + (base) + (t) * 16); dst[1] = *(const f32x4*)(Mx + (base) + (t) * 16 + 4); dst[2] = *(const f32x4*)(Mx + (base) + (t) * 16 + 8); dst[3] = *(const f32x4*)(Mx + (base) + (t) * 16 + 12); } while (0)
; __device__ unsigned long long rwkv2_phase(const Params& p, unsigned char* smem) {
;     ...
;                         { const u16* VT = (const u16*)(S1b + (cm % 3) * 10560 + 8192);
;                           const bf16x8 makf = *(const bf16x8*)(Mxb + 1024 + l15 * 32 + 8 * lq);
; #pragma unroll
;                           for (int nt = 0; nt < 4; ++nt) { u32x4 vz = {0u, 0u, 0u, 0u}; if (lq < 2) vz = *(const u32x4*)(VT + (16 * nt + l15) * 16 + 8 * lq);
;                               const f32x4 d = MFMA16(makf, as_frag(vz), ((f32x4){0.f, 0.f, 0.f, 0.f}));
; #pragma unroll
;                               for (int r = 0; r < 4; ++r) MVs[(4 * lq + r) * 64 + 16 * nt + l15] = d[r]; }
;                           asm volatile("s_waitcnt lgkmcnt(0)" ::: "memory"); }
;                         float vh[16], x0[16];
; #pragma unroll
;                         for (int t = 0; t < 16; ++t) x0[t] = MVs[t * 64 + lane];
;                         f32x4 rc[4], rn[4];
;                         TRI_ROW(rc, 0, 0);
; #pragma unroll
;                         for (int t = 0; t < 16; ++t) { if (t < 15) TRI_ROW(rn, 0, t + 1);
;                             float pa[4] = {x0[t], 0.f, 0.f, 0.f};
; #pragma unroll
;                             for (int s = 0; s + 1 < t; ++s) pa[s & 3] += rc[s >> 2][s & 3] * vh[s];
;                             float acc = (pa[0] + pa[1]) + (pa[2] + pa[3]);
;                             if (t >= 1) acc += rc[(t - 1) >> 2][(t - 1) & 3] * vh[t - 1];
;                             vh[t] = acc; Vh[t * 64 + lane] = acc;
.LBB0_908:
	s_andn2_b64 vcc, exec, s[26:27]
	s_cbranch_vccnz .LBB0_922
	s_mul_i32 s26, s69, 0x4200
	s_add_i32 s28, s26, 0
	s_add_i32 s28, s28, 0x19d40
	s_mov_b64 s[26:27], -1
	s_and_b64 vcc, exec, s[60:61]
	s_cbranch_vccz .LBB0_919
	s_mul_hi_i32 s26, s68, 0x55555556
	s_lshr_b32 s27, s26, 31
	s_add_i32 s26, s26, s27
	v_lshlrev_b32_e32 v3, 6, v72
	v_lshlrev_b32_e32 v4, 4, v73
	v_readlane_b32 s16, v251, 63
	s_mul_i32 s26, s26, 3
	s_sub_i32 s26, s68, s26
	v_add3_u32 v3, s16, v3, v4
	ds_read_b128 v[42:45], v3
	s_mulk_i32 s26, 0x2940
	s_add_i32 s26, s26, 0
	s_add_i32 s26, s26, 0xe380
	v_lshlrev_b32_e32 v3, 5, v72
	v_cmp_gt_i32_e32 vcc, 2, v73
	v_add3_u32 v3, s26, v3, v4
	v_mov_b32_e32 v186, 0
	v_mov_b32_e32 v187, 0
	v_mov_b32_e32 v188, 0
	v_mov_b32_e32 v189, 0
	v_mov_b32_e32 v190, 0
	v_mov_b32_e32 v191, 0
	v_mov_b32_e32 v192, 0
	v_mov_b32_e32 v193, 0
	v_mov_b32_e32 v194, 0
	v_mov_b32_e32 v195, 0
	v_mov_b32_e32 v196, 0
	v_mov_b32_e32 v197, 0
	v_mov_b32_e32 v198, 0
	v_mov_b32_e32 v199, 0
	v_mov_b32_e32 v200, 0
	v_mov_b32_e32 v201, 0
	s_and_saveexec_b64 s[26:27], vcc
	ds_read_b128 v[186:189], v3 offset:8192
	ds_read_b128 v[190:193], v3 offset:8704
	ds_read_b128 v[194:197], v3 offset:9216
	ds_read_b128 v[198:201], v3 offset:9728
	s_or_b64 exec, exec, s[26:27]
	v_lshlrev_b32_e32 v4, 10, v73
	v_lshlrev_b32_e32 v5, 2, v72
	v_readlane_b32 s16, v250, 1
	s_waitcnt lgkmcnt(0)
	v_mfma_f32_16x16x32_bf16 v[186:189], v[42:45], v[186:189], 0
	v_mfma_f32_16x16x32_bf16 v[190:193], v[42:45], v[190:193], 0
	v_mfma_f32_16x16x32_bf16 v[194:197], v[42:45], v[194:197], 0
	v_mfma_f32_16x16x32_bf16 v[198:201], v[42:45], v[198:201], 0
	v_add3_u32 v4, s16, v4, v5
	v_lshlrev_b32_e32 v3, 2, v74
	v_add_u32_e32 v5, 0, v3
	v_add_u32_e32 v75, s28, v3
	s_nop 3
	ds_write2st64_b32 v4, v186, v187 offset1:1
	ds_write2st64_b32 v4, v188, v189 offset0:2 offset1:3
	ds_write2_b32 v4, v190, v191 offset0:16 offset1:80
	ds_write2_b32 v4, v192, v193 offset0:144 offset1:208
	ds_write2_b32 v4, v194, v195 offset0:32 offset1:96
	ds_write2_b32 v4, v196, v197 offset0:160 offset1:224
	ds_write2_b32 v4, v198, v199 offset0:48 offset1:112
	ds_write2_b32 v4, v200, v201 offset0:176 offset1:240
	s_waitcnt lgkmcnt(0)
	v_add_u32_e32 v42, 0x18b40, v5
	ds_read_b32 v76, v42
	ds_read_b32 v77, v42 offset:256
	ds_read_b32 v78, v42 offset:512
	ds_read_b32 v79, v42 offset:768
	ds_read_b32 v80, v42 offset:1024
	ds_read_b32 v81, v42 offset:1280
	ds_read_b32 v82, v42 offset:1536
	ds_read_b32 v83, v42 offset:1792
	ds_read_b32 v84, v42 offset:2048
	ds_read_b32 v85, v42 offset:2304
	ds_read_b32 v86, v42 offset:2560
	ds_read_b32 v87, v42 offset:2816
	ds_read_b32 v88, v42 offset:3072
	ds_read_b32 v89, v42 offset:3328
	ds_read_b32 v90, v42 offset:3584
	ds_read_b32 v91, v42 offset:3840
	v_mov_b32_e32 v234, 0x15f40
	ds_read_b128 v[186:189], v234 offset:64
	ds_read_b128 v[190:193], v234 offset:128
	ds_read_b128 v[194:197], v234 offset:192
	ds_read_b128 v[198:201], v234 offset:256
	ds_read_b128 v[202:205], v234 offset:320
	ds_read_b128 v[206:209], v234 offset:336
	ds_read_b128 v[210:213], v234 offset:384
	ds_read_b128 v[214:217], v234 offset:400
	ds_read_b128 v[218:221], v234 offset:448
	ds_read_b128 v[222:225], v234 offset:464
	ds_read_b128 v[226:229], v234 offset:512
	ds_read_b128 v[230:233], v234 offset:528
	s_waitcnt lgkmcnt(12)
	s_waitcnt lgkmcnt(11)
	v_fmac_f32_e32 v77, v186, v76
	ds_read_b128 v[186:189], v234 offset:576
	s_waitcnt lgkmcnt(11)
	v_fmac_f32_e32 v78, v190, v76
	v_fmac_f32_e32 v78, v191, v77
	ds_read_b128 v[190:193], v234 offset:592
	s_waitcnt lgkmcnt(11)
	v_fmac_f32_e32 v79, v194, v76
	v_fmac_f32_e32 v79, v195, v77
	v_fmac_f32_e32 v79, v196, v78
	ds_read_b128 v[194:197], v234 offset:608
	s_waitcnt lgkmcnt(11)
	v_fmac_f32_e32 v80, v198, v76
	v_fmac_f32_e32 v80, v199, v77
	v_fmac_f32_e32 v80, v200, v78
	v_fmac_f32_e32 v80, v201, v79
	ds_read_b128 v[198:201], v234 offset:640
	s_waitcnt lgkmcnt(11)
	v_fmac_f32_e32 v81, v202, v76
	v_fmac_f32_e32 v81, v203, v77
	v_fmac_f32_e32 v81, v204, v78
	v_fmac_f32_e32 v81, v205, v79
	ds_read_b128 v[202:205], v234 offset:656
	s_waitcnt lgkmcnt(11)
	v_fmac_f32_e32 v81, v206, v80
	ds_read_b128 v[206:209], v234 offset:672
	s_waitcnt lgkmcnt(11)
	v_fmac_f32_e32 v82, v210, v76
	v_fmac_f32_e32 v82, v211, v77
	v_fmac_f32_e32 v82, v212, v78
	v_fmac_f32_e32 v82, v213, v79
	ds_read_b128 v[210:213], v234 offset:704
	s_waitcnt lgkmcnt(11)
	v_fmac_f32_e32 v82, v214, v80
	v_fmac_f32_e32 v82, v215, v81
	ds_read_b128 v[214:217], v234 offset:720
	s_waitcnt lgkmcnt(11)
	v_fmac_f32_e32 v83, v218, v76
	v_fmac_f32_e32 v83, v219, v77
	v_fmac_f32_e32 v83, v220, v78
	v_fmac_f32_e32 v83, v221, v79
	ds_read_b128 v[218:221], v234 offset:736
	s_waitcnt lgkmcnt(11)
	v_fmac_f32_e32 v83, v222, v80
	v_fmac_f32_e32 v83, v223, v81
	v_fmac_f32_e32 v83, v224, v82
	ds_read_b128 v[222:225], v234 offset:768
	s_waitcnt lgkmcnt(11)
; __device__ __forceinline__ unsigned pk2(float lo, float hi) { unsigned r; asm volatile("v_cvt_pk_bf16_f32 %0, %1, %2" : "=v"(r) : "v"(lo), "v"(hi)); return r; }
; #define TRI_ROW(dst, base, t) do { dst[0] = *(const f32x4*)(Mx + (base) + (t) * 16); dst[1] = *(const f32x4*)(Mx + (base) + (t) * 16 + 4); dst[2] = *(const f32x4*)(Mx + (base) + (t) * 16 + 8); dst[3] = *(const f32x4*)(Mx + (base) + (t) * 16 + 12); } while (0)
; #define TRI_NEXT(rc, rn) do { _Pragma("unroll") for (int i_ = 0; i_ < 4; ++i_) rc[i_] = rn[i_]; asm volatile("" ::: "memory"); } while (0)
; __device__ unsigned long long rwkv2_phase(const Params& p, unsigned char* smem) {
;     ...
;                         float vh[16], x0[16];
; #pragma unroll
;                         for (int t = 0; t < 16; ++t) x0[t] = MVs[t * 64 + lane];
;                         f32x4 rc[4], rn[4];
;                         TRI_ROW(rc, 0, 0);
; #pragma unroll
;                         for (int t = 0; t < 16; ++t) { if (t < 15) TRI_ROW(rn, 0, t + 1);
;                             float pa[4] = {x0[t], 0.f, 0.f, 0.f};
; #pragma unroll
;                             for (int s = 0; s + 1 < t; ++s) pa[s & 3] += rc[s >> 2][s & 3] * vh[s];
;                             float acc = (pa[0] + pa[1]) + (pa[2] + pa[3]);
;                             if (t >= 1) acc += rc[(t - 1) >> 2][(t - 1) & 3] * vh[t - 1];
;                             vh[t] = acc; Vh[t * 64 + lane] = acc;
;                             TRI_NEXT(rc, rn); }
;                         { u32x4 q0, q1; q0.x = pk2(vh[0], vh[1]); q0.y = pk2(vh[2], vh[3]); q0.z = pk2(vh[4], vh[5]); q0.w = pk2(vh[6], vh[7]);
;                           q1.x = pk2(vh[8], vh[9]); q1.y = pk2(vh[10], vh[11]); q1.z = pk2(vh[12], vh[13]); q1.w = pk2(vh[14], vh[15]);
;                           *(u32x4*)(VhT + lane * 16) = q0; *(u32x4*)(VhT + lane * 16 + 8) = q1; }
	v_fmac_f32_e32 v84, v226, v76
	v_fmac_f32_e32 v84, v227, v77
	v_fmac_f32_e32 v84, v228, v78
	v_fmac_f32_e32 v84, v229, v79
	ds_read_b128 v[226:229], v234 offset:784
	s_waitcnt lgkmcnt(11)
	v_fmac_f32_e32 v84, v230, v80
	v_fmac_f32_e32 v84, v231, v81
	v_fmac_f32_e32 v84, v232, v82
	v_fmac_f32_e32 v84, v233, v83
	ds_read_b128 v[230:233], v234 offset:800
	s_waitcnt lgkmcnt(11)
	v_fmac_f32_e32 v85, v186, v76
	v_fmac_f32_e32 v85, v187, v77
	v_fmac_f32_e32 v85, v188, v78
	v_fmac_f32_e32 v85, v189, v79
	ds_read_b128 v[186:189], v234 offset:832
	s_waitcnt lgkmcnt(11)
	v_fmac_f32_e32 v85, v190, v80
	v_fmac_f32_e32 v85, v191, v81
	v_fmac_f32_e32 v85, v192, v82
	v_fmac_f32_e32 v85, v193, v83
	ds_read_b128 v[190:193], v234 offset:848
	s_waitcnt lgkmcnt(11)
	v_fmac_f32_e32 v85, v194, v84
	ds_read_b128 v[194:197], v234 offset:864
	s_waitcnt lgkmcnt(11)
	v_fmac_f32_e32 v86, v198, v76
	v_fmac_f32_e32 v86, v199, v77
	v_fmac_f32_e32 v86, v200, v78
	v_fmac_f32_e32 v86, v201, v79
	ds_read_b128 v[198:201], v234 offset:880
	s_waitcnt lgkmcnt(11)
	v_fmac_f32_e32 v86, v202, v80
	v_fmac_f32_e32 v86, v203, v81
	v_fmac_f32_e32 v86, v204, v82
	v_fmac_f32_e32 v86, v205, v83
	ds_read_b128 v[202:205], v234 offset:896
	s_waitcnt lgkmcnt(11)
	v_fmac_f32_e32 v86, v206, v84
	v_fmac_f32_e32 v86, v207, v85
	ds_read_b128 v[206:209], v234 offset:912
	s_waitcnt lgkmcnt(11)
	v_fmac_f32_e32 v87, v210, v76
	v_fmac_f32_e32 v87, v211, v77
	v_fmac_f32_e32 v87, v212, v78
	v_fmac_f32_e32 v87, v213, v79
	ds_read_b128 v[210:213], v234 offset:928
	s_waitcnt lgkmcnt(11)
	v_fmac_f32_e32 v87, v214, v80
	v_fmac_f32_e32 v87, v215, v81
	v_fmac_f32_e32 v87, v216, v82
	v_fmac_f32_e32 v87, v217, v83
	ds_read_b128 v[214:217], v234 offset:944
	s_waitcnt lgkmcnt(11)
	v_fmac_f32_e32 v87, v218, v84
	v_fmac_f32_e32 v87, v219, v85
	v_fmac_f32_e32 v87, v220, v86
	ds_read_b128 v[218:221], v234 offset:960
	s_waitcnt lgkmcnt(11)
	v_fmac_f32_e32 v88, v222, v76
	v_fmac_f32_e32 v88, v223, v77
	v_fmac_f32_e32 v88, v224, v78
	v_fmac_f32_e32 v88, v225, v79
	ds_read_b128 v[222:225], v234 offset:976
	s_waitcnt lgkmcnt(11)
	v_fmac_f32_e32 v88, v226, v80
	v_fmac_f32_e32 v88, v227, v81
	v_fmac_f32_e32 v88, v228, v82
	v_fmac_f32_e32 v88, v229, v83
	ds_read_b128 v[226:229], v234 offset:992
	s_waitcnt lgkmcnt(11)
	v_fmac_f32_e32 v88, v230, v84
	v_fmac_f32_e32 v88, v231, v85
	v_fmac_f32_e32 v88, v232, v86
	v_fmac_f32_e32 v88, v233, v87
	ds_read_b128 v[230:233], v234 offset:1008
	s_waitcnt lgkmcnt(11)
	v_fmac_f32_e32 v89, v186, v76
	v_fmac_f32_e32 v89, v187, v77
	v_fmac_f32_e32 v89, v188, v78
	v_fmac_f32_e32 v89, v189, v79
	s_waitcnt lgkmcnt(10)
	v_fmac_f32_e32 v89, v190, v80
	v_fmac_f32_e32 v89, v191, v81
	v_fmac_f32_e32 v89, v192, v82
	v_fmac_f32_e32 v89, v193, v83
	s_waitcnt lgkmcnt(9)
	v_fmac_f32_e32 v89, v194, v84
	v_fmac_f32_e32 v89, v195, v85
	v_fmac_f32_e32 v89, v196, v86
	v_fmac_f32_e32 v89, v197, v87
	s_waitcnt lgkmcnt(8)
	v_fmac_f32_e32 v89, v198, v88
	s_waitcnt lgkmcnt(7)
	v_fmac_f32_e32 v90, v202, v76
	v_fmac_f32_e32 v90, v203, v77
	v_fmac_f32_e32 v90, v204, v78
	v_fmac_f32_e32 v90, v205, v79
	s_waitcnt lgkmcnt(6)
	v_fmac_f32_e32 v90, v206, v80
	v_fmac_f32_e32 v90, v207, v81
	v_fmac_f32_e32 v90, v208, v82
	v_fmac_f32_e32 v90, v209, v83
	s_waitcnt lgkmcnt(5)
	v_fmac_f32_e32 v90, v210, v84
	v_fmac_f32_e32 v90, v211, v85
	v_fmac_f32_e32 v90, v212, v86
	v_fmac_f32_e32 v90, v213, v87
	s_waitcnt lgkmcnt(4)
	v_fmac_f32_e32 v90, v214, v88
	v_fmac_f32_e32 v90, v215, v89
	s_waitcnt lgkmcnt(3)
	v_fmac_f32_e32 v91, v218, v76
	v_fmac_f32_e32 v91, v219, v77
	v_fmac_f32_e32 v91, v220, v78
	v_fmac_f32_e32 v91, v221, v79
	s_waitcnt lgkmcnt(2)
	v_fmac_f32_e32 v91, v222, v80
	v_fmac_f32_e32 v91, v223, v81
	v_fmac_f32_e32 v91, v224, v82
	v_fmac_f32_e32 v91, v225, v83
	s_waitcnt lgkmcnt(1)
	v_fmac_f32_e32 v91, v226, v84
	v_fmac_f32_e32 v91, v227, v85
	v_fmac_f32_e32 v91, v228, v86
	v_fmac_f32_e32 v91, v229, v87
	s_waitcnt lgkmcnt(0)
	v_fmac_f32_e32 v91, v230, v88
	v_fmac_f32_e32 v91, v231, v89
	v_fmac_f32_e32 v91, v232, v90
	ds_write_b32 v75, v76 offset:4608
	ds_write_b32 v75, v77 offset:4864
	ds_write_b32 v75, v78 offset:5120
	ds_write_b32 v75, v79 offset:5376
	ds_write_b32 v75, v80 offset:5632
	ds_write_b32 v75, v81 offset:5888
	ds_write_b32 v75, v82 offset:6144
	ds_write_b32 v75, v83 offset:6400
	ds_write_b32 v75, v84 offset:6656
	ds_write_b32 v75, v85 offset:6912
	ds_write_b32 v75, v86 offset:7168
	ds_write_b32 v75, v87 offset:7424
	ds_write_b32 v75, v88 offset:7680
	ds_write_b32 v75, v89 offset:7936
	ds_write_b32 v75, v90 offset:8192
	ds_write_b32 v75, v91 offset:8448
	v_cvt_pk_bf16_f32 v42, v76, v77
	v_cvt_pk_bf16_f32 v43, v78, v79
	v_cvt_pk_bf16_f32 v44, v80, v81
	v_cvt_pk_bf16_f32 v45, v82, v83
	v_cvt_pk_bf16_f32 v46, v84, v85
	v_cvt_pk_bf16_f32 v47, v86, v87
	v_cvt_pk_bf16_f32 v48, v88, v89
	v_cvt_pk_bf16_f32 v49, v90, v91
	s_mov_b64 s[26:27], 0
